# v51 + retention tile epilogue: the six gate loads hipcc serialised behind the output stores are issued together up front (free VGPR pairs, counted vmcnt)
# speedup vs baseline: 1.0048x; 1.0048x over previous
; DI float bflo(unsigned u) { return __uint_as_float(u << 16); }
; DI float bfhi(unsigned u) { return __uint_as_float(u & 0xffff0000u); }
; DI float sigmoidf(float x) { return __builtin_amdgcn_rcpf(1.f + __expf(-x)); }
; DI void ret_tile(const Params& p, int b, int h, int c, bf16_t* lds) {
;     ...
; #pragma unroll
;   for (int nt = 0; nt < 2; ++nt) {
;     float ss = 0.f;
; #pragma unroll
;     for (int et = 0; et < 8; ++et)
; #pragma unroll
;       for (int j = 0; j < 4; ++j) ss += acc[et][nt][j] * acc[et][nt][j];
;     ss += shx(ss, 16, lane);
;     ss += shx(ss, 32, lane);
;     const float rs = rsqrtf(ss * (1.f / 128.f) + 1e-6f);
;     const int n = 32 * w + nt * 16 + col;
;     bf16_t* zr = zc + (size_t)n * ZS;
; #pragma unroll
;     for (int et = 0; et < 8; ++et) {
;       const int e0 = et * 16 + quad * 4;
;       uint2 gv = *(const uint2*)(zr + C_RG + h * 128 + e0);
;       float g0 = bflo(gv.x), g1 = bfhi(gv.x), g2 = bflo(gv.y), g3 = bfhi(gv.y);
;       uint2 o;
;       o.x = pack2(acc[et][nt][0] * rs * g0 * sigmoidf(g0), acc[et][nt][1] * rs * g1 * sigmoidf(g1));
;       o.y = pack2(acc[et][nt][2] * rs * g2 * sigmoidf(g2), acc[et][nt][3] * rs * g3 * sigmoidf(g3));
;       *(uint2*)(zr + C_RQ + h * 128 + e0) = o;
;     }
.LBB0_447:
	s_or_b64 exec, exec, s[0:1]
	s_lshl_b32 s28, s6, 1
	v_lshl_add_u64 v[38:39], v[166:167], 0, s[28:29]
	s_mov_b64 s[2:3], 0x1630
	v_lshl_add_u64 v[40:41], v[38:39], 0, s[2:3]
	v_lshlrev_b32_e32 v80, 1, v180
	v_mov_b32_e32 v81, v1
	v_lshl_add_u64 v[38:39], v[40:41], 0, v[80:81]
	v_lshlrev_b32_e32 v78, 1, v178
	v_mov_b32_e32 v79, v1
	global_load_dwordx2 v[94:95], v[38:39], off
	v_lshl_add_u64 v[38:39], v[40:41], 0, v[78:79]
	v_lshlrev_b32_e32 v76, 1, v176
	v_mov_b32_e32 v77, v1
	global_load_dwordx2 v[96:97], v[38:39], off
	v_lshl_add_u64 v[38:39], v[40:41], 0, v[76:77]
	global_load_dwordx2 v[106:107], v[38:39], off
	v_lshlrev_b32_e32 v72, 1, v174
	v_mov_b32_e32 v73, v1
	v_lshl_add_u64 v[38:39], v[40:41], 0, v[72:73]
	global_load_dwordx2 v[120:121], v[38:39], off
	v_lshlrev_b32_e32 v0, 1, v0
	v_lshlrev_b32_e32 v74, 1, v172
	v_mov_b32_e32 v75, v1
	v_lshlrev_b32_e32 v70, 1, v170
	v_mov_b32_e32 v71, v1
	v_lshlrev_b32_e32 v38, 1, v168
	v_mov_b32_e32 v39, v1
	v_lshl_add_u64 v[98:99], v[40:41], 0, v[0:1]
	v_lshl_add_u64 v[100:101], v[40:41], 0, v[74:75]
	v_lshl_add_u64 v[102:103], v[40:41], 0, v[70:71]
	v_lshl_add_u64 v[104:105], v[40:41], 0, v[38:39]
	global_load_dwordx2 v[40:41], v[98:99], off
	global_load_dwordx2 v[134:135], v[100:101], off
	global_load_dwordx2 v[144:145], v[102:103], off
	global_load_dwordx2 v[152:153], v[104:105], off
	v_mov_b32_e32 v166, v7
	v_mov_b32_e32 v167, v3
	v_mov_b32_e32 v157, v2
	v_pk_mul_f32 v[166:167], v[166:167], v[166:167]
	v_pk_mul_f32 v[84:85], v[46:47], v[46:47]
	v_pk_mul_f32 v[170:171], v[14:15], v[14:15]
	v_pk_mul_f32 v[82:83], v[48:49], v[48:49]
	v_pk_mul_f32 v[168:169], v[16:17], v[16:17]
	v_pk_mul_f32 v[88:89], v[42:43], v[42:43]
	v_pk_mul_f32 v[172:173], v[10:11], v[10:11]
	v_pk_mul_f32 v[86:87], v[44:45], v[44:45]
	v_lshlrev_b32_e32 v90, 2, v210
	v_xor_b32_e32 v155, 64, v90
	v_xor_b32_e32 v163, 0x80, v90
	s_brev_b32 s0, 60
	v_lshl_add_u64 v[92:93], v[160:161], 0, v[80:81]
	v_lshl_add_u64 v[90:91], v[160:161], 0, v[78:79]
	v_lshl_add_u64 v[128:129], v[160:161], 0, v[72:73]
	v_lshl_add_u64 v[140:141], v[160:161], 0, v[74:75]
	v_lshl_add_u64 v[148:149], v[160:161], 0, v[70:71]
	s_waitcnt vmcnt(7)
	v_and_b32_e32 v105, 0xffff0000, v94
	v_lshlrev_b32_e32 v104, 16, v94
	v_lshlrev_b32_e32 v102, 16, v95
	v_and_b32_e32 v103, 0xffff0000, v95
	s_waitcnt vmcnt(6)
	v_lshlrev_b32_e32 v100, 16, v96
	v_mul_f32_e32 v109, 0xbfb8aa3b, v103
	s_waitcnt vmcnt(5)
	v_lshlrev_b32_e32 v94, 16, v107
	v_and_b32_e32 v95, 0xffff0000, v107
	v_mul_f32_e32 v107, 0xbfb8aa3b, v105
	v_exp_f32_e32 v107, v107
	v_mul_f32_e32 v110, 0xbfb8aa3b, v100
	v_exp_f32_e32 v109, v109
	v_exp_f32_e32 v110, v110
	v_and_b32_e32 v101, 0xffff0000, v96
	v_lshlrev_b32_e32 v98, 16, v97
	v_and_b32_e32 v99, 0xffff0000, v97
	v_lshlrev_b32_e32 v96, 16, v106
	v_and_b32_e32 v97, 0xffff0000, v106
	v_mul_f32_e32 v106, 0xbfb8aa3b, v104
	v_mul_f32_e32 v115, 0xbfb8aa3b, v97
	v_exp_f32_e32 v106, v106
	v_add_f32_e32 v107, 1.0, v107
	v_mul_f32_e32 v108, 0xbfb8aa3b, v102
	v_mul_f32_e32 v114, 0xbfb8aa3b, v96
	v_exp_f32_e32 v115, v115
	v_add_f32_e32 v109, 1.0, v109
	v_rcp_f32_e32 v133, v107
	v_mul_f32_e32 v107, 0xbfb8aa3b, v94
	v_mul_f32_e32 v111, 0xbfb8aa3b, v101
	v_exp_f32_e32 v108, v108
	v_exp_f32_e32 v114, v114
	v_add_f32_e32 v110, 1.0, v110
	v_rcp_f32_e32 v127, v109
	v_exp_f32_e32 v107, v107
	v_mul_f32_e32 v109, 0xbfb8aa3b, v95
	v_exp_f32_e32 v111, v111
	v_rcp_f32_e32 v118, v110
	v_exp_f32_e32 v110, v109
	v_add_f32_e32 v106, 1.0, v106
	v_rcp_f32_e32 v132, v106
	v_add_f32_e32 v106, 1.0, v115
	v_add_f32_e32 v108, 1.0, v108
	v_add_f32_e32 v114, 1.0, v114
	v_rcp_f32_e32 v109, v106
	v_add_f32_e32 v106, 1.0, v107
	v_add_f32_e32 v111, 1.0, v111
	v_rcp_f32_e32 v126, v108
	v_rcp_f32_e32 v108, v114
	v_rcp_f32_e32 v114, v106
	v_add_f32_e32 v106, 1.0, v110
	s_waitcnt vmcnt(4)
	v_lshlrev_b32_e32 v110, 16, v120
	v_rcp_f32_e32 v119, v111
	v_and_b32_e32 v111, 0xffff0000, v120
	v_mul_f32_e32 v107, 0xbfb8aa3b, v110
	v_exp_f32_e32 v120, v107
	v_mul_f32_e32 v107, 0xbfb8aa3b, v111
	v_exp_f32_e32 v123, v107
	v_rcp_f32_e32 v115, v106
	v_lshlrev_b32_e32 v106, 16, v121
	v_and_b32_e32 v107, 0xffff0000, v121
	v_add_f32_e32 v120, 1.0, v120
	v_mul_f32_e32 v121, 0xbfb8aa3b, v106
	v_rcp_f32_e32 v122, v120
	v_add_f32_e32 v120, 1.0, v123
	v_exp_f32_e32 v121, v121
	v_mul_f32_e32 v123, 0xbfb8aa3b, v107
	v_exp_f32_e32 v124, v123
	v_rcp_f32_e32 v123, v120
	v_add_f32_e32 v120, 1.0, v121
	v_rcp_f32_e32 v130, v120
	v_add_f32_e32 v120, 1.0, v124
	s_waitcnt vmcnt(2)
	v_lshlrev_b32_e32 v124, 16, v134
	v_and_b32_e32 v125, 0xffff0000, v134
	v_mul_f32_e32 v121, 0xbfb8aa3b, v124
	v_exp_f32_e32 v134, v121
	v_mul_f32_e32 v121, 0xbfb8aa3b, v125
	v_exp_f32_e32 v137, v121
	v_rcp_f32_e32 v131, v120
	v_lshlrev_b32_e32 v120, 16, v135
	v_and_b32_e32 v121, 0xffff0000, v135
	v_add_f32_e32 v134, 1.0, v134
	v_mul_f32_e32 v135, 0xbfb8aa3b, v120
	v_rcp_f32_e32 v136, v134
	v_add_f32_e32 v134, 1.0, v137
	v_exp_f32_e32 v135, v135
	v_mul_f32_e32 v137, 0xbfb8aa3b, v121
	v_exp_f32_e32 v138, v137
	v_rcp_f32_e32 v137, v134
	v_add_f32_e32 v134, 1.0, v135
	v_rcp_f32_e32 v142, v134
	v_add_f32_e32 v134, 1.0, v138
	s_waitcnt vmcnt(1)
	v_lshlrev_b32_e32 v138, 16, v144
	v_and_b32_e32 v139, 0xffff0000, v144
	v_mul_f32_e32 v135, 0xbfb8aa3b, v138
	v_exp_f32_e32 v144, v135
	v_mul_f32_e32 v135, 0xbfb8aa3b, v139
	v_exp_f32_e32 v146, v135
	v_rcp_f32_e32 v143, v134
	v_lshlrev_b32_e32 v134, 16, v145
	v_and_b32_e32 v135, 0xffff0000, v145
	v_add_f32_e32 v145, 1.0, v146
	v_mul_f32_e32 v146, 0xbfb8aa3b, v134
	v_exp_f32_e32 v146, v146
	v_mul_f32_e32 v147, 0xbfb8aa3b, v135
	v_exp_f32_e32 v147, v147
	v_mul_f32_e32 v112, 0xbfb8aa3b, v98
	v_add_f32_e32 v146, 1.0, v146
	v_rcp_f32_e32 v150, v146
	v_add_f32_e32 v146, 1.0, v147
	v_rcp_f32_e32 v151, v146
	s_waitcnt vmcnt(0)
; DI void ret_tile(const Params& p, int b, int h, int c, bf16_t* lds) {
;     ...
;   for (int nt = 0; nt < 2; ++nt) {
;     float ss = 0.f;
; #pragma unroll
;     for (int et = 0; et < 8; ++et)
; #pragma unroll
;       for (int j = 0; j < 4; ++j) ss += acc[et][nt][j] * acc[et][nt][j];
;     ss += shx(ss, 16, lane);
;     ss += shx(ss, 32, lane);
;     const float rs = rsqrtf(ss * (1.f / 128.f) + 1e-6f);
	v_lshlrev_b32_e32 v146, 16, v152
	v_mul_f32_e32 v147, 0xbfb8aa3b, v146
	v_exp_f32_e32 v154, v147
	v_and_b32_e32 v147, 0xffff0000, v152
	v_mul_f32_e32 v156, 0xbfb8aa3b, v147
	v_exp_f32_e32 v174, v156
	v_mov_b32_e32 v156, v6
	v_pk_fma_f32 v[156:157], v[156:157], v[156:157], v[166:167]
	v_mov_b32_e32 v166, v8
	v_mov_b32_e32 v167, v4
	v_pk_fma_f32 v[156:157], v[166:167], v[166:167], v[156:157]
	v_mov_b32_e32 v166, v9
	v_mov_b32_e32 v167, v5
	v_pk_fma_f32 v[156:157], v[166:167], v[166:167], v[156:157]
	v_mov_b32_e32 v166, v34
	v_mov_b32_e32 v167, v66
	v_pk_fma_f32 v[156:157], v[166:167], v[166:167], v[156:157]
	v_mov_b32_e32 v166, v35
	v_mov_b32_e32 v167, v67
	v_pk_fma_f32 v[156:157], v[166:167], v[166:167], v[156:157]
	v_mov_b32_e32 v166, v36
	v_mov_b32_e32 v167, v68
	v_pk_fma_f32 v[156:157], v[166:167], v[166:167], v[156:157]
	v_mov_b32_e32 v166, v37
	v_mov_b32_e32 v167, v69
	v_pk_fma_f32 v[156:157], v[166:167], v[166:167], v[156:157]
	v_mov_b32_e32 v166, v30
	v_mov_b32_e32 v167, v62
	v_pk_fma_f32 v[156:157], v[166:167], v[166:167], v[156:157]
	v_mov_b32_e32 v166, v31
	v_mov_b32_e32 v167, v63
	v_pk_fma_f32 v[156:157], v[166:167], v[166:167], v[156:157]
	v_mov_b32_e32 v166, v32
	v_mov_b32_e32 v167, v64
	v_pk_fma_f32 v[156:157], v[166:167], v[166:167], v[156:157]
	v_mov_b32_e32 v166, v33
	v_mov_b32_e32 v167, v65
	v_pk_fma_f32 v[156:157], v[166:167], v[166:167], v[156:157]
	v_mov_b32_e32 v166, v26
	v_mov_b32_e32 v167, v58
	v_pk_fma_f32 v[156:157], v[166:167], v[166:167], v[156:157]
	v_mov_b32_e32 v166, v27
	v_mov_b32_e32 v167, v59
	v_pk_fma_f32 v[156:157], v[166:167], v[166:167], v[156:157]
	v_mov_b32_e32 v166, v28
	v_mov_b32_e32 v167, v60
	v_pk_fma_f32 v[156:157], v[166:167], v[166:167], v[156:157]
	v_mov_b32_e32 v166, v29
	v_mov_b32_e32 v167, v61
	v_pk_fma_f32 v[156:157], v[166:167], v[166:167], v[156:157]
	v_mov_b32_e32 v166, v22
	v_mov_b32_e32 v167, v54
	v_pk_fma_f32 v[156:157], v[166:167], v[166:167], v[156:157]
	v_mov_b32_e32 v166, v23
	v_mov_b32_e32 v167, v55
	v_pk_fma_f32 v[156:157], v[166:167], v[166:167], v[156:157]
	v_mov_b32_e32 v166, v24
	v_mov_b32_e32 v167, v56
	v_pk_fma_f32 v[156:157], v[166:167], v[166:167], v[156:157]
	v_mov_b32_e32 v166, v25
	v_mov_b32_e32 v167, v57
	v_pk_fma_f32 v[156:157], v[166:167], v[166:167], v[156:157]
	v_mov_b32_e32 v166, v18
	v_mov_b32_e32 v167, v50
	v_pk_fma_f32 v[156:157], v[166:167], v[166:167], v[156:157]
	v_mov_b32_e32 v166, v19
	v_mov_b32_e32 v167, v51
	v_pk_fma_f32 v[156:157], v[166:167], v[166:167], v[156:157]
	v_mov_b32_e32 v166, v20
	v_mov_b32_e32 v167, v52
	v_pk_fma_f32 v[156:157], v[166:167], v[166:167], v[156:157]
	v_mov_b32_e32 v166, v21
	v_mov_b32_e32 v167, v53
	v_pk_fma_f32 v[156:157], v[166:167], v[166:167], v[156:157]
	v_mov_b32_e32 v166, v170
	v_mov_b32_e32 v167, v84
	v_pk_add_f32 v[156:157], v[166:167], v[156:157]
	v_mov_b32_e32 v84, v171
	v_pk_add_f32 v[84:85], v[84:85], v[156:157]
	v_mov_b32_e32 v156, v168
	v_mov_b32_e32 v157, v82
	v_pk_add_f32 v[84:85], v[156:157], v[84:85]
	v_mov_b32_e32 v82, v169
	v_pk_add_f32 v[82:83], v[82:83], v[84:85]
	v_mov_b32_e32 v84, v172
	v_mov_b32_e32 v85, v88
	v_pk_mul_f32 v[166:167], v[12:13], v[12:13]
	v_pk_add_f32 v[82:83], v[84:85], v[82:83]
	v_mov_b32_e32 v88, v173
	v_pk_add_f32 v[82:83], v[88:89], v[82:83]
	v_mov_b32_e32 v84, v166
	v_mov_b32_e32 v85, v86
	v_pk_add_f32 v[82:83], v[84:85], v[82:83]
	v_mov_b32_e32 v86, v167
	v_pk_add_f32 v[82:83], v[86:87], v[82:83]
	ds_bpermute_b32 v85, v155, v83
	ds_bpermute_b32 v84, v155, v82
	v_lshlrev_b32_e32 v152, 16, v153
	v_and_b32_e32 v153, 0xffff0000, v153
	v_add_f32_e32 v86, 1.0, v174
	v_mul_f32_e32 v113, 0xbfb8aa3b, v99
	s_waitcnt lgkmcnt(0)
	v_pk_add_f32 v[82:83], v[82:83], v[84:85]
	ds_bpermute_b32 v85, v163, v83
	ds_bpermute_b32 v84, v163, v82
	v_rcp_f32_e32 v155, v86
	v_mul_f32_e32 v86, 0xbfb8aa3b, v152
	v_mul_f32_e32 v87, 0xbfb8aa3b, v153
	v_exp_f32_e32 v112, v112
	s_waitcnt lgkmcnt(0)
; DI float bflo(unsigned u) { return __uint_as_float(u << 16); }
; DI float bfhi(unsigned u) { return __uint_as_float(u & 0xffff0000u); }
; DI float sigmoidf(float x) { return __builtin_amdgcn_rcpf(1.f + __expf(-x)); }
; DI void ret_tile(const Params& p, int b, int h, int c, bf16_t* lds) {
;     ...
;     ss += shx(ss, 16, lane);
;     ss += shx(ss, 32, lane);
;     const float rs = rsqrtf(ss * (1.f / 128.f) + 1e-6f);
;     const int n = 32 * w + nt * 16 + col;
;     bf16_t* zr = zc + (size_t)n * ZS;
; #pragma unroll
;     for (int et = 0; et < 8; ++et) {
;       const int e0 = et * 16 + quad * 4;
;       uint2 gv = *(const uint2*)(zr + C_RG + h * 128 + e0);
;       float g0 = bflo(gv.x), g1 = bfhi(gv.x), g2 = bflo(gv.y), g3 = bfhi(gv.y);
;       uint2 o;
;       o.x = pack2(acc[et][nt][0] * rs * g0 * sigmoidf(g0), acc[et][nt][1] * rs * g1 * sigmoidf(g1));
;       o.y = pack2(acc[et][nt][2] * rs * g2 * sigmoidf(g2), acc[et][nt][3] * rs * g3 * sigmoidf(g3));
;       *(uint2*)(zr + C_RQ + h * 128 + e0) = o;
;     }
	v_pk_add_f32 v[82:83], v[82:83], v[84:85]
	v_mov_b32_e32 v84, 0x358637bd
	v_pk_fma_f32 v[84:85], v[82:83], s[0:1], v[84:85] op_sel_hi:[1,0,0]
	v_exp_f32_e32 v113, v113
	v_mul_f32_e32 v82, 0x4b800000, v85
	v_cmp_gt_f32_e32 vcc, s9, v85
	v_exp_f32_e32 v86, v86
	v_exp_f32_e32 v87, v87
	v_cndmask_b32_e32 v82, v85, v82, vcc
	v_rsq_f32_e32 v82, v82
	v_add_f32_e32 v112, 1.0, v112
	v_add_f32_e32 v113, 1.0, v113
	v_add_f32_e32 v144, 1.0, v144
	v_add_f32_e32 v154, 1.0, v154
	v_add_f32_e32 v86, 1.0, v86
	v_add_f32_e32 v83, 1.0, v87
	v_rcp_f32_e32 v116, v112
	v_rcp_f32_e32 v117, v113
	v_rcp_f32_e32 v144, v144
	v_rcp_f32_e32 v145, v145
	v_rcp_f32_e32 v154, v154
	v_rcp_f32_e32 v86, v86
	v_rcp_f32_e32 v87, v83
	v_mul_f32_e32 v83, 0x45800000, v82
	v_cndmask_b32_e32 v82, v82, v83, vcc
	v_pk_mul_f32 v[66:67], v[66:67], v[82:83] op_sel_hi:[1,0]
	v_pk_mul_f32 v[68:69], v[68:69], v[82:83] op_sel_hi:[1,0]
	v_pk_mul_f32 v[62:63], v[62:63], v[82:83] op_sel_hi:[1,0]
	v_pk_mul_f32 v[64:65], v[64:65], v[82:83] op_sel_hi:[1,0]
	v_pk_mul_f32 v[58:59], v[58:59], v[82:83] op_sel_hi:[1,0]
	v_pk_mul_f32 v[60:61], v[60:61], v[82:83] op_sel_hi:[1,0]
	v_pk_mul_f32 v[54:55], v[54:55], v[82:83] op_sel_hi:[1,0]
	v_pk_mul_f32 v[56:57], v[56:57], v[82:83] op_sel_hi:[1,0]
	v_pk_mul_f32 v[50:51], v[50:51], v[82:83] op_sel_hi:[1,0]
	v_pk_mul_f32 v[52:53], v[52:53], v[82:83] op_sel_hi:[1,0]
	v_pk_mul_f32 v[46:47], v[46:47], v[82:83] op_sel_hi:[1,0]
	v_pk_mul_f32 v[48:49], v[48:49], v[82:83] op_sel_hi:[1,0]
	v_pk_mul_f32 v[42:43], v[42:43], v[82:83] op_sel_hi:[1,0]
	v_pk_mul_f32 v[44:45], v[44:45], v[82:83] op_sel_hi:[1,0]
	v_pk_mul_f32 v[66:67], v[66:67], v[104:105]
	v_pk_mul_f32 v[68:69], v[68:69], v[102:103]
	v_pk_mul_f32 v[62:63], v[62:63], v[100:101]
	v_pk_mul_f32 v[64:65], v[64:65], v[98:99]
	v_pk_mul_f32 v[58:59], v[58:59], v[96:97]
	v_pk_mul_f32 v[60:61], v[60:61], v[94:95]
	v_pk_mul_f32 v[54:55], v[54:55], v[110:111]
	v_pk_mul_f32 v[56:57], v[56:57], v[106:107]
	v_pk_mul_f32 v[50:51], v[50:51], v[124:125]
	v_pk_mul_f32 v[52:53], v[52:53], v[120:121]
	v_pk_mul_f32 v[46:47], v[46:47], v[138:139]
	v_pk_mul_f32 v[48:49], v[48:49], v[134:135]
	v_pk_mul_f32 v[42:43], v[42:43], v[146:147]
	v_pk_mul_f32 v[44:45], v[44:45], v[152:153]
	v_pk_mul_f32 v[66:67], v[132:133], v[66:67]
	v_pk_mul_f32 v[68:69], v[126:127], v[68:69]
	v_pk_mul_f32 v[62:63], v[118:119], v[62:63]
	v_pk_mul_f32 v[64:65], v[116:117], v[64:65]
	v_pk_mul_f32 v[58:59], v[108:109], v[58:59]
	v_pk_mul_f32 v[60:61], v[114:115], v[60:61]
	v_pk_mul_f32 v[54:55], v[122:123], v[54:55]
	v_pk_mul_f32 v[56:57], v[130:131], v[56:57]
	v_pk_mul_f32 v[50:51], v[136:137], v[50:51]
	v_pk_mul_f32 v[52:53], v[142:143], v[52:53]
	v_pk_mul_f32 v[46:47], v[144:145], v[46:47]
	v_pk_mul_f32 v[48:49], v[150:151], v[48:49]
	v_pk_mul_f32 v[42:43], v[42:43], v[154:155]
	v_pk_mul_f32 v[44:45], v[44:45], v[86:87]
	v_lshl_add_u64 v[112:113], v[160:161], 0, v[76:77]
	v_lshl_add_u64 v[88:89], v[160:161], 0, v[38:39]
	v_cvt_pk_bf16_f32 v66, v66, v67
	v_cvt_pk_bf16_f32 v67, v68, v69
	v_cvt_pk_bf16_f32 v62, v62, v63
	v_cvt_pk_bf16_f32 v63, v64, v65
	v_cvt_pk_bf16_f32 v58, v58, v59
	v_cvt_pk_bf16_f32 v59, v60, v61
	v_cvt_pk_bf16_f32 v54, v54, v55
	v_cvt_pk_bf16_f32 v55, v56, v57
	v_cvt_pk_bf16_f32 v50, v50, v51
	v_cvt_pk_bf16_f32 v51, v52, v53
	v_cvt_pk_bf16_f32 v46, v46, v47
	v_cvt_pk_bf16_f32 v47, v48, v49
	v_cvt_pk_bf16_f32 v42, v42, v43
	v_cvt_pk_bf16_f32 v43, v44, v45
	global_store_dwordx2 v[92:93], v[66:67], off offset:2608
	global_store_dwordx2 v[90:91], v[62:63], off offset:2608
	global_store_dwordx2 v[112:113], v[58:59], off offset:2608
	global_store_dwordx2 v[128:129], v[54:55], off offset:2608
	global_store_dwordx2 v[140:141], v[50:51], off offset:2608
	global_store_dwordx2 v[148:149], v[46:47], off offset:2608
	global_store_dwordx2 v[88:89], v[42:43], off offset:2608
	v_lshl_add_u64 v[42:43], v[164:165], 0, s[28:29]
	v_lshl_add_u64 v[46:47], v[42:43], 0, s[2:3]
	v_lshl_add_u64 v[42:43], v[46:47], 0, v[80:81]
	global_load_dwordx2 v[48:49], v[42:43], off
	v_mul_f32_e32 v42, 0x4b800000, v84
	v_cmp_gt_f32_e32 vcc, s9, v84
	v_pk_mul_f32 v[2:3], v[2:3], v[82:83] op_sel_hi:[1,0]
	v_pk_mul_f32 v[4:5], v[4:5], v[82:83] op_sel_hi:[1,0]
	v_cndmask_b32_e32 v42, v84, v42, vcc
	v_rsq_f32_e32 v44, v42
	v_lshl_add_u64 v[42:43], v[46:47], 0, v[0:1]
	global_load_dwordx2 v[42:43], v[42:43], off
	v_lshl_add_u64 v[114:115], v[46:47], 0, v[78:79]
	global_load_dwordx2 v[114:115], v[114:115], off
	v_lshl_add_u64 v[116:117], v[46:47], 0, v[76:77]
	global_load_dwordx2 v[116:117], v[116:117], off
	v_lshl_add_u64 v[118:119], v[46:47], 0, v[72:73]
	global_load_dwordx2 v[118:119], v[118:119], off
	v_lshl_add_u64 v[120:121], v[46:47], 0, v[74:75]
	global_load_dwordx2 v[120:121], v[120:121], off
	v_lshl_add_u64 v[122:123], v[46:47], 0, v[70:71]
	global_load_dwordx2 v[122:123], v[122:123], off
	v_lshl_add_u64 v[124:125], v[46:47], 0, v[38:39]
	global_load_dwordx2 v[124:125], v[124:125], off
	s_mov_b64 s[0:1], 0
	v_mul_f32_e32 v45, 0x45800000, v44
	v_cndmask_b32_e32 v44, v44, v45, vcc
	s_waitcnt vmcnt(7)
	v_lshlrev_b32_e32 v50, 16, v48
	v_mul_f32_e32 v45, 0xbfb8aa3b, v50
	v_and_b32_e32 v51, 0xffff0000, v48
	v_exp_f32_e32 v45, v45
	v_mul_f32_e32 v52, 0xbfb8aa3b, v51
	v_exp_f32_e32 v53, v52
	v_lshlrev_b32_e32 v48, 16, v49
	v_add_f32_e32 v45, 1.0, v45
	v_rcp_f32_e32 v52, v45
	v_pk_mul_f32 v[34:35], v[34:35], v[44:45] op_sel_hi:[1,0]
	v_add_f32_e32 v45, 1.0, v53
	v_and_b32_e32 v49, 0xffff0000, v49
	v_rcp_f32_e32 v53, v45
	v_mul_f32_e32 v45, 0xbfb8aa3b, v48
	v_pk_mul_f32 v[34:35], v[34:35], v[50:51]
	v_exp_f32_e32 v45, v45
	v_mul_f32_e32 v50, 0xbfb8aa3b, v49
	v_exp_f32_e32 v51, v50
	v_pk_mul_f32 v[34:35], v[34:35], v[52:53]
	v_add_f32_e32 v45, 1.0, v45
	v_rcp_f32_e32 v50, v45
	v_add_f32_e32 v45, 1.0, v51
	v_rcp_f32_e32 v51, v45
	v_pk_mul_f32 v[36:37], v[36:37], v[44:45] op_sel_hi:[1,0]
	v_cvt_pk_bf16_f32 v34, v34, v35
	v_pk_mul_f32 v[36:37], v[36:37], v[48:49]
	s_nop 0
	v_pk_mul_f32 v[36:37], v[36:37], v[50:51]
	s_nop 0
	v_cvt_pk_bf16_f32 v35, v36, v37
	v_lshl_add_u64 v[36:37], v[158:159], 0, v[80:81]
	global_store_dwordx2 v[36:37], v[34:35], off offset:2608


; DI float bflo(unsigned u) { return __uint_as_float(u << 16); }
; DI float bfhi(unsigned u) { return __uint_as_float(u & 0xffff0000u); }
; DI float sigmoidf(float x) { return __builtin_amdgcn_rcpf(1.f + __expf(-x)); }
; DI void ret_tile(const Params& p, int b, int h, int c, bf16_t* lds) {
;     ...
;     for (int et = 0; et < 8; ++et) {
;       const int e0 = et * 16 + quad * 4;
;       uint2 gv = *(const uint2*)(zr + C_RG + h * 128 + e0);
;       float g0 = bflo(gv.x), g1 = bfhi(gv.x), g2 = bflo(gv.y), g3 = bfhi(gv.y);
;       uint2 o;
;       o.x = pack2(acc[et][nt][0] * rs * g0 * sigmoidf(g0), acc[et][nt][1] * rs * g1 * sigmoidf(g1));
;       o.y = pack2(acc[et][nt][2] * rs * g2 * sigmoidf(g2), acc[et][nt][3] * rs * g3 * sigmoidf(g3));
;       *(uint2*)(zr + C_RQ + h * 128 + e0) = o;
;     }
	s_waitcnt vmcnt(6)
	v_lshlrev_b32_e32 v36, 16, v114
	v_mul_f32_e32 v37, 0xbfb8aa3b, v36
	v_exp_f32_e32 v45, v37
	v_and_b32_e32 v37, 0xffff0000, v114
	v_mul_f32_e32 v48, 0xbfb8aa3b, v37
	v_exp_f32_e32 v49, v48
	v_add_f32_e32 v45, 1.0, v45
	v_pk_mul_f32 v[30:31], v[30:31], v[44:45] op_sel_hi:[1,0]
	v_lshlrev_b32_e32 v34, 16, v115
	v_and_b32_e32 v35, 0xffff0000, v115
	v_pk_mul_f32 v[30:31], v[30:31], v[36:37]
	v_add_f32_e32 v36, 1.0, v49
	v_rcp_f32_e32 v49, v36
	v_mul_f32_e32 v36, 0xbfb8aa3b, v34
	v_mul_f32_e32 v37, 0xbfb8aa3b, v35
	v_exp_f32_e32 v36, v36
	v_exp_f32_e32 v37, v37
	v_rcp_f32_e32 v48, v45
	v_pk_mul_f32 v[32:33], v[32:33], v[44:45] op_sel_hi:[1,0]
	v_add_f32_e32 v36, 1.0, v36
	v_add_f32_e32 v37, 1.0, v37
	v_rcp_f32_e32 v36, v36
	v_rcp_f32_e32 v37, v37
	v_pk_mul_f32 v[32:33], v[32:33], v[34:35]
	v_pk_mul_f32 v[30:31], v[30:31], v[48:49]
	v_pk_mul_f32 v[26:27], v[26:27], v[44:45] op_sel_hi:[1,0]
	v_pk_mul_f32 v[32:33], v[32:33], v[36:37]
	v_cvt_pk_bf16_f32 v30, v30, v31
	v_cvt_pk_bf16_f32 v31, v32, v33
	v_lshl_add_u64 v[32:33], v[158:159], 0, v[78:79]
	global_store_dwordx2 v[32:33], v[30:31], off offset:2608


; DI float bflo(unsigned u) { return __uint_as_float(u << 16); }
; DI float bfhi(unsigned u) { return __uint_as_float(u & 0xffff0000u); }
; DI float sigmoidf(float x) { return __builtin_amdgcn_rcpf(1.f + __expf(-x)); }
; DI void ret_tile(const Params& p, int b, int h, int c, bf16_t* lds) {
;     ...
;     for (int et = 0; et < 8; ++et) {
;       const int e0 = et * 16 + quad * 4;
;       uint2 gv = *(const uint2*)(zr + C_RG + h * 128 + e0);
;       float g0 = bflo(gv.x), g1 = bfhi(gv.x), g2 = bflo(gv.y), g3 = bfhi(gv.y);
;       uint2 o;
;       o.x = pack2(acc[et][nt][0] * rs * g0 * sigmoidf(g0), acc[et][nt][1] * rs * g1 * sigmoidf(g1));
;       o.y = pack2(acc[et][nt][2] * rs * g2 * sigmoidf(g2), acc[et][nt][3] * rs * g3 * sigmoidf(g3));
;       *(uint2*)(zr + C_RQ + h * 128 + e0) = o;
;     }
	v_pk_mul_f32 v[28:29], v[28:29], v[44:45] op_sel_hi:[1,0]
	v_pk_mul_f32 v[22:23], v[22:23], v[44:45] op_sel_hi:[1,0]
	v_pk_mul_f32 v[24:25], v[24:25], v[44:45] op_sel_hi:[1,0]
	v_pk_mul_f32 v[18:19], v[18:19], v[44:45] op_sel_hi:[1,0]
	v_pk_mul_f32 v[20:21], v[20:21], v[44:45] op_sel_hi:[1,0]
	v_pk_mul_f32 v[14:15], v[14:15], v[44:45] op_sel_hi:[1,0]
	v_pk_mul_f32 v[16:17], v[16:17], v[44:45] op_sel_hi:[1,0]
	v_pk_mul_f32 v[6:7], v[6:7], v[44:45] op_sel_hi:[1,0]
	v_pk_mul_f32 v[8:9], v[8:9], v[44:45] op_sel_hi:[1,0]
	v_pk_mul_f32 v[10:11], v[10:11], v[44:45] op_sel_hi:[1,0]
	v_pk_mul_f32 v[12:13], v[12:13], v[44:45] op_sel_hi:[1,0]
	s_waitcnt vmcnt(6)
	v_lshlrev_b32_e32 v32, 16, v116
	v_mul_f32_e32 v33, 0xbfb8aa3b, v32
	v_exp_f32_e32 v34, v33
	v_and_b32_e32 v33, 0xffff0000, v116
	v_mul_f32_e32 v35, 0xbfb8aa3b, v33
	v_exp_f32_e32 v35, v35
	v_lshlrev_b32_e32 v30, 16, v117
	v_and_b32_e32 v31, 0xffff0000, v117
	v_pk_mul_f32 v[26:27], v[26:27], v[32:33]
	v_add_f32_e32 v32, 1.0, v35
	v_rcp_f32_e32 v35, v32
	v_mul_f32_e32 v32, 0xbfb8aa3b, v30
	v_mul_f32_e32 v33, 0xbfb8aa3b, v31
	v_exp_f32_e32 v32, v32
	v_exp_f32_e32 v33, v33
	v_add_f32_e32 v34, 1.0, v34
	v_rcp_f32_e32 v34, v34
	v_add_f32_e32 v32, 1.0, v32
	v_add_f32_e32 v33, 1.0, v33
	v_rcp_f32_e32 v32, v32
	v_rcp_f32_e32 v33, v33
	v_pk_mul_f32 v[28:29], v[28:29], v[30:31]
	v_pk_mul_f32 v[26:27], v[26:27], v[34:35]
	v_pk_mul_f32 v[28:29], v[28:29], v[32:33]
	v_cvt_pk_bf16_f32 v26, v26, v27
	v_cvt_pk_bf16_f32 v27, v28, v29
	v_lshl_add_u64 v[28:29], v[158:159], 0, v[76:77]
	global_store_dwordx2 v[28:29], v[26:27], off offset:2608


; DI float bflo(unsigned u) { return __uint_as_float(u << 16); }
; DI float bfhi(unsigned u) { return __uint_as_float(u & 0xffff0000u); }
; DI float sigmoidf(float x) { return __builtin_amdgcn_rcpf(1.f + __expf(-x)); }
; DI void ret_tile(const Params& p, int b, int h, int c, bf16_t* lds) {
;     ...
;     for (int et = 0; et < 8; ++et) {
;       const int e0 = et * 16 + quad * 4;
;       uint2 gv = *(const uint2*)(zr + C_RG + h * 128 + e0);
;       float g0 = bflo(gv.x), g1 = bfhi(gv.x), g2 = bflo(gv.y), g3 = bfhi(gv.y);
;       uint2 o;
;       o.x = pack2(acc[et][nt][0] * rs * g0 * sigmoidf(g0), acc[et][nt][1] * rs * g1 * sigmoidf(g1));
;       o.y = pack2(acc[et][nt][2] * rs * g2 * sigmoidf(g2), acc[et][nt][3] * rs * g3 * sigmoidf(g3));
;       *(uint2*)(zr + C_RQ + h * 128 + e0) = o;
;     }
	s_waitcnt vmcnt(6)
	v_lshlrev_b32_e32 v28, 16, v118
	v_mul_f32_e32 v29, 0xbfb8aa3b, v28
	v_exp_f32_e32 v30, v29
	v_and_b32_e32 v29, 0xffff0000, v118
	v_mul_f32_e32 v31, 0xbfb8aa3b, v29
	v_exp_f32_e32 v31, v31
	v_lshlrev_b32_e32 v26, 16, v119
	v_and_b32_e32 v27, 0xffff0000, v119
	v_pk_mul_f32 v[22:23], v[22:23], v[28:29]
	v_add_f32_e32 v28, 1.0, v31
	v_rcp_f32_e32 v31, v28
	v_mul_f32_e32 v28, 0xbfb8aa3b, v26
	v_mul_f32_e32 v29, 0xbfb8aa3b, v27
	v_exp_f32_e32 v28, v28
	v_exp_f32_e32 v29, v29
	v_add_f32_e32 v30, 1.0, v30
	v_rcp_f32_e32 v30, v30
	v_add_f32_e32 v28, 1.0, v28
	v_add_f32_e32 v29, 1.0, v29
	v_rcp_f32_e32 v28, v28
	v_rcp_f32_e32 v29, v29
	v_pk_mul_f32 v[24:25], v[24:25], v[26:27]
	v_pk_mul_f32 v[22:23], v[22:23], v[30:31]

; DI float sigmoidf(float x) { return __builtin_amdgcn_rcpf(1.f + __expf(-x)); }
; DI void ret_tile(const Params& p, int b, int h, int c, bf16_t* lds) {
;     ...
;       o.x = pack2(acc[et][nt][0] * rs * g0 * sigmoidf(g0), acc[et][nt][1] * rs * g1 * sigmoidf(g1));
;       o.y = pack2(acc[et][nt][2] * rs * g2 * sigmoidf(g2), acc[et][nt][3] * rs * g3 * sigmoidf(g3));
;       *(uint2*)(zr + C_RQ + h * 128 + e0) = o;
	v_pk_mul_f32 v[24:25], v[24:25], v[28:29]
	v_cvt_pk_bf16_f32 v22, v22, v23
	v_cvt_pk_bf16_f32 v23, v24, v25
	v_lshl_add_u64 v[24:25], v[158:159], 0, v[72:73]
	global_store_dwordx2 v[24:25], v[22:23], off offset:2608


; DI float bflo(unsigned u) { return __uint_as_float(u << 16); }
; DI float bfhi(unsigned u) { return __uint_as_float(u & 0xffff0000u); }
; DI float sigmoidf(float x) { return __builtin_amdgcn_rcpf(1.f + __expf(-x)); }
; DI void ret_tile(const Params& p, int b, int h, int c, bf16_t* lds) {
;     ...
;     for (int et = 0; et < 8; ++et) {
;       const int e0 = et * 16 + quad * 4;
;       uint2 gv = *(const uint2*)(zr + C_RG + h * 128 + e0);
;       float g0 = bflo(gv.x), g1 = bfhi(gv.x), g2 = bflo(gv.y), g3 = bfhi(gv.y);
;       uint2 o;
;       o.x = pack2(acc[et][nt][0] * rs * g0 * sigmoidf(g0), acc[et][nt][1] * rs * g1 * sigmoidf(g1));
;       o.y = pack2(acc[et][nt][2] * rs * g2 * sigmoidf(g2), acc[et][nt][3] * rs * g3 * sigmoidf(g3));
;       *(uint2*)(zr + C_RQ + h * 128 + e0) = o;
;     }
	v_lshl_add_u64 v[24:25], v[158:159], 0, v[74:75]
	s_waitcnt vmcnt(6)
	v_lshlrev_b32_e32 v28, 16, v120
	v_and_b32_e32 v29, 0xffff0000, v120
	v_lshlrev_b32_e32 v22, 16, v121
	v_and_b32_e32 v23, 0xffff0000, v121
	v_mul_f32_e32 v30, 0xbfb8aa3b, v28
	v_mul_f32_e32 v31, 0xbfb8aa3b, v29
	v_mul_f32_e32 v32, 0xbfb8aa3b, v22
	v_mul_f32_e32 v33, 0xbfb8aa3b, v23
	v_exp_f32_e32 v30, v30
	v_exp_f32_e32 v31, v31
	v_exp_f32_e32 v32, v32
	v_exp_f32_e32 v33, v33
	v_add_f32_e32 v30, 1.0, v30
	v_add_f32_e32 v31, 1.0, v31
	v_add_f32_e32 v32, 1.0, v32
	v_add_f32_e32 v33, 1.0, v33
	v_rcp_f32_e32 v30, v30
	v_rcp_f32_e32 v31, v31
	v_rcp_f32_e32 v32, v32
	v_rcp_f32_e32 v33, v33
	v_pk_mul_f32 v[18:19], v[18:19], v[28:29]
	v_pk_mul_f32 v[20:21], v[20:21], v[22:23]
	v_pk_mul_f32 v[18:19], v[18:19], v[30:31]
	v_pk_mul_f32 v[20:21], v[20:21], v[32:33]
	v_cvt_pk_bf16_f32 v18, v18, v19
	v_cvt_pk_bf16_f32 v19, v20, v21
	global_store_dwordx2 v[24:25], v[18:19], off offset:2608

; DI void ret_tile(const Params& p, int b, int h, int c, bf16_t* lds) {
;     ...
;     bf16_t* zr = zc + (size_t)n * ZS;
; #pragma unroll
;     for (int et = 0; et < 8; ++et) {
;       const int e0 = et * 16 + quad * 4;
;       uint2 gv = *(const uint2*)(zr + C_RG + h * 128 + e0);
	v_lshl_add_u64 v[20:21], v[158:159], 0, v[70:71]

; DI float bflo(unsigned u) { return __uint_as_float(u << 16); }
; DI float bfhi(unsigned u) { return __uint_as_float(u & 0xffff0000u); }
; DI float sigmoidf(float x) { return __builtin_amdgcn_rcpf(1.f + __expf(-x)); }
; DI void ret_tile(const Params& p, int b, int h, int c, bf16_t* lds) {
;     ...
;     for (int et = 0; et < 8; ++et) {
;       const int e0 = et * 16 + quad * 4;
;       uint2 gv = *(const uint2*)(zr + C_RG + h * 128 + e0);
;       float g0 = bflo(gv.x), g1 = bfhi(gv.x), g2 = bflo(gv.y), g3 = bfhi(gv.y);
;       uint2 o;
;       o.x = pack2(acc[et][nt][0] * rs * g0 * sigmoidf(g0), acc[et][nt][1] * rs * g1 * sigmoidf(g1));
;       o.y = pack2(acc[et][nt][2] * rs * g2 * sigmoidf(g2), acc[et][nt][3] * rs * g3 * sigmoidf(g3));
;       *(uint2*)(zr + C_RQ + h * 128 + e0) = o;
;     }
	s_waitcnt vmcnt(6)
	v_lshlrev_b32_e32 v24, 16, v122
	v_and_b32_e32 v25, 0xffff0000, v122
	v_lshlrev_b32_e32 v18, 16, v123
	v_and_b32_e32 v19, 0xffff0000, v123
	v_mul_f32_e32 v26, 0xbfb8aa3b, v24
	v_mul_f32_e32 v27, 0xbfb8aa3b, v25
	v_mul_f32_e32 v28, 0xbfb8aa3b, v18
	v_mul_f32_e32 v29, 0xbfb8aa3b, v19
	v_exp_f32_e32 v26, v26
	v_exp_f32_e32 v27, v27
	v_exp_f32_e32 v28, v28
	v_exp_f32_e32 v29, v29
	v_add_f32_e32 v26, 1.0, v26
	v_add_f32_e32 v27, 1.0, v27
	v_add_f32_e32 v28, 1.0, v28
	v_add_f32_e32 v29, 1.0, v29
	v_rcp_f32_e32 v26, v26
	v_rcp_f32_e32 v27, v27
	v_rcp_f32_e32 v28, v28
	v_rcp_f32_e32 v29, v29
	v_pk_mul_f32 v[14:15], v[14:15], v[24:25]
	v_pk_mul_f32 v[16:17], v[16:17], v[18:19]
	v_pk_mul_f32 v[14:15], v[14:15], v[26:27]
	v_pk_mul_f32 v[16:17], v[16:17], v[28:29]
	v_cvt_pk_bf16_f32 v14, v14, v15
	v_cvt_pk_bf16_f32 v15, v16, v17
	global_store_dwordx2 v[20:21], v[14:15], off offset:2608

; DI float bflo(unsigned u) { return __uint_as_float(u << 16); }
; DI float bfhi(unsigned u) { return __uint_as_float(u & 0xffff0000u); }
; DI float sigmoidf(float x) { return __builtin_amdgcn_rcpf(1.f + __expf(-x)); }
; DI void ret_tile(const Params& p, int b, int h, int c, bf16_t* lds) {
;     ...
;     for (int et = 0; et < 8; ++et) {
;       const int e0 = et * 16 + quad * 4;
;       uint2 gv = *(const uint2*)(zr + C_RG + h * 128 + e0);
;       float g0 = bflo(gv.x), g1 = bfhi(gv.x), g2 = bflo(gv.y), g3 = bfhi(gv.y);
;       uint2 o;
;       o.x = pack2(acc[et][nt][0] * rs * g0 * sigmoidf(g0), acc[et][nt][1] * rs * g1 * sigmoidf(g1));
;       o.y = pack2(acc[et][nt][2] * rs * g2 * sigmoidf(g2), acc[et][nt][3] * rs * g3 * sigmoidf(g3));
;       *(uint2*)(zr + C_RQ + h * 128 + e0) = o;
;     }
	v_lshlrev_b32_e32 v22, 16, v40
	v_and_b32_e32 v23, 0xffff0000, v40
	v_lshlrev_b32_e32 v24, 16, v41
	v_and_b32_e32 v25, 0xffff0000, v41
	v_lshl_add_u64 v[16:17], v[160:161], 0, v[0:1]
	v_lshl_add_u64 v[18:19], v[158:159], 0, v[0:1]
	v_mul_f32_e32 v0, 0xbfb8aa3b, v22
	v_mul_f32_e32 v26, 0xbfb8aa3b, v23
	v_mul_f32_e32 v27, 0xbfb8aa3b, v24
	v_mul_f32_e32 v28, 0xbfb8aa3b, v25
	v_exp_f32_e32 v0, v0
	v_exp_f32_e32 v26, v26
	v_exp_f32_e32 v27, v27
	v_exp_f32_e32 v28, v28
	v_add_f32_e32 v0, 1.0, v0
	v_add_f32_e32 v29, 1.0, v26
	v_add_f32_e32 v30, 1.0, v27
	v_add_f32_e32 v31, 1.0, v28
	v_rcp_f32_e32 v26, v0
	v_rcp_f32_e32 v27, v29
	v_rcp_f32_e32 v28, v30
	v_rcp_f32_e32 v29, v31
	v_pk_mul_f32 v[2:3], v[2:3], v[22:23]
	v_pk_mul_f32 v[4:5], v[4:5], v[24:25]
	v_pk_mul_f32 v[2:3], v[26:27], v[2:3]
	v_pk_mul_f32 v[4:5], v[28:29], v[4:5]
	v_cvt_pk_bf16_f32 v2, v2, v3
	v_cvt_pk_bf16_f32 v3, v4, v5
	global_store_dwordx2 v[16:17], v[2:3], off offset:2608
	v_lshlrev_b32_e32 v2, 16, v42
	v_and_b32_e32 v3, 0xffff0000, v42
	v_lshlrev_b32_e32 v4, 16, v43
	v_and_b32_e32 v5, 0xffff0000, v43
	v_mul_f32_e32 v0, 0xbfb8aa3b, v2
	v_mul_f32_e32 v16, 0xbfb8aa3b, v3
	v_mul_f32_e32 v17, 0xbfb8aa3b, v4
	v_mul_f32_e32 v22, 0xbfb8aa3b, v5
	v_exp_f32_e32 v0, v0
	v_exp_f32_e32 v16, v16
	v_exp_f32_e32 v17, v17
	v_exp_f32_e32 v22, v22
	v_add_f32_e32 v0, 1.0, v0
	v_add_f32_e32 v23, 1.0, v16
	v_add_f32_e32 v24, 1.0, v17
	v_add_f32_e32 v25, 1.0, v22
	v_rcp_f32_e32 v16, v0
	v_rcp_f32_e32 v17, v23
	v_rcp_f32_e32 v22, v24
	v_rcp_f32_e32 v23, v25
	v_pk_mul_f32 v[2:3], v[6:7], v[2:3]
	v_pk_mul_f32 v[4:5], v[8:9], v[4:5]
	v_pk_mul_f32 v[2:3], v[16:17], v[2:3]
	v_pk_mul_f32 v[4:5], v[22:23], v[4:5]
	v_cvt_pk_bf16_f32 v2, v2, v3
	v_cvt_pk_bf16_f32 v3, v4, v5
	global_store_dwordx2 v[18:19], v[2:3], off offset:2608
	v_lshl_add_u64 v[20:21], v[158:159], 0, v[38:39]
	s_waitcnt vmcnt(8)
	v_lshlrev_b32_e32 v2, 16, v124
	v_and_b32_e32 v3, 0xffff0000, v124
	v_lshlrev_b32_e32 v4, 16, v125
	v_and_b32_e32 v5, 0xffff0000, v125
	v_mul_f32_e32 v0, 0xbfb8aa3b, v2
	v_mul_f32_e32 v6, 0xbfb8aa3b, v3
	v_mul_f32_e32 v7, 0xbfb8aa3b, v4
	v_mul_f32_e32 v8, 0xbfb8aa3b, v5
	v_exp_f32_e32 v0, v0
	v_exp_f32_e32 v6, v6
	v_exp_f32_e32 v7, v7
	v_exp_f32_e32 v8, v8
	v_add_f32_e32 v0, 1.0, v0
	v_add_f32_e32 v9, 1.0, v6
	v_add_f32_e32 v14, 1.0, v7
	v_add_f32_e32 v15, 1.0, v8
	v_rcp_f32_e32 v6, v0
	v_rcp_f32_e32 v7, v9
	v_rcp_f32_e32 v8, v14
	v_rcp_f32_e32 v9, v15
	v_pk_mul_f32 v[2:3], v[10:11], v[2:3]
	v_pk_mul_f32 v[4:5], v[12:13], v[4:5]
	v_pk_mul_f32 v[2:3], v[2:3], v[6:7]
	v_pk_mul_f32 v[4:5], v[4:5], v[8:9]
	v_cvt_pk_bf16_f32 v2, v2, v3
	v_cvt_pk_bf16_f32 v3, v4, v5
	global_store_dwordx2 v[20:21], v[2:3], off offset:2608
